# cvhost: LDS transpose right after barrier A, pack + sector stores + next loads moved to the mid-tile point (start of the next P.V), relaxed step-B wait
# baseline (speedup 1.0000x reference)
; #define GAS __attribute__((address_space(1)))
; __device__ __forceinline__ unsigned cvt_pk_bf16(float lo, float hi) { unsigned r; asm volatile("v_cvt_pk_bf16_f32 %0, %1, %2" : "=v"(r) : "v"(lo), "v"(hi)); return r; }
; template <int NB>
; __device__ __forceinline__ void p0_batch(int it0, int stride, int lane, const P0Ptrs& a) {
;     ...
;     for (int q = 0; q < NB; ++q) {
;         const float gs = d[q].gs; const bool hk = d[q].ks != nullptr;
;         const f32x4 t0 = hk ? s0[q] * gs : (f32x4){gs, gs, gs, gs}, t1 = hk ? s1[q] * gs : (f32x4){gs, gs, gs, gs};
; #pragma unroll
;         for (int i = 0; i < 4; ++i) { v[q][i] *= t0[i]; v[q][4 + i] *= t1[i]; }
;         if (d[q].dst) {
; #pragma unroll
;             for (int e = 0; e < 4; ++e) { u32x4 o; o.x = cvt_pk_bf16(v[q][0][e], v[q][1][e]); o.y = cvt_pk_bf16(v[q][2][e], v[q][3][e]); o.z = cvt_pk_bf16(v[q][4][e], v[q][5][e]); o.w = cvt_pk_bf16(v[q][6][e], v[q][7][e]);
;                 *(GAS u32x4*)(d[q].dst + (size_t)e * d[q].ldt) = o; } }
;     }
.LBB0_760:
	s_cmp_gt_u32 s87, 20
	s_cbranch_scc1 .Lcv_done
	s_cmp_eq_u32 s87, 0
	s_cbranch_scc1 .Lcv_nocons
	v_and_b32_e32 v207, 63, v0
	v_lshrrev_b32_e32 v208, 2, v207
	v_and_b32_e32 v209, 3, v207
	v_lshlrev_b32_e32 v210, 3, v209
	v_mad_u32_u24 v210, v208, s91, v210
	s_lshl_b32 s98, s91, 4
	s_add_u32 s98, s92, s98
	s_addc_u32 s99, s93, 0
	s_waitcnt lgkmcnt(0)
	v_cvt_pk_bf16_f32 v238, v238, v239
	v_cvt_pk_bf16_f32 v239, v240, v241
	v_cvt_pk_bf16_f32 v242, v242, v243
	v_cvt_pk_bf16_f32 v243, v244, v245
	global_store_dwordx2 v210, v[238:239], s[92:93]
	global_store_dwordx2 v210, v[242:243], s[98:99]
	s_add_u32 s92, s92, 32
	s_addc_u32 s93, s93, 0

; template <int NB>
; __device__ __forceinline__ void p0_batch(int it0, int stride, int lane, const P0Ptrs& a) {
;     f32x4 v[NB][8], s0[NB], s1[NB]; P0Desc d[NB];
; #pragma unroll
;     for (int q = 0; q < NB; ++q) { const bool ok = it0 < NFAST / 4; d[q] = p0_desc(p0_super(ok ? it0 : 0, q), lane, a); if (!ok) d[q].dst = nullptr;
; #pragma unroll
;         for (int i = 0; i < 8; ++i) v[q][i] = __builtin_nontemporal_load((const f32x4*)(d[q].src + (size_t)i * d[q].nsrc));
;         const float* kp = d[q].ks ? d[q].ks : a.ffn_g;
;         s0[q] = *(const f32x4*)(kp); s1[q] = *(const f32x4*)(kp + 4); }
.Lcv_s2done:
.Lcv_loads:
	v_and_b32_e32 v207, 63, v0
	v_lshrrev_b32_e32 v208, 2, v207
	v_and_b32_e32 v209, 3, v207
	v_lshlrev_b32_e32 v209, 4, v209
	v_mad_u32_u24 v211, v208, s90, v209
	v_lshlrev_b32_e32 v212, 2, v208
	s_lshl_b32 s98, s90, 4
	global_load_dwordx4 v[238:241], v211, s[88:89] nt
	global_load_dwordx4 v[242:245], v211, s[88:89] offset:64 nt
	global_load_dword v237, v212, s[94:95]
	s_add_u32 s88, s88, s98
	s_addc_u32 s89, s89, 0
	s_add_u32 s94, s94, 64
	s_addc_u32 s95, s95, 0
	s_and_b32 s98, s87, 3
	s_cmp_lg_u32 s98, 3
	s_cbranch_scc1 .Lcv_inc
	s_cmp_gt_u32 s87, 18
	s_cbranch_scc1 .Lcv_inc
	s_add_i32 s99, s32, 1
	s_movk_i32 s98, 0x78
	s_cmp_lt_u32 s99, 7
	s_cselect_b32 s98, 0x60, s98
	s_cmp_eq_u32 s99, 0
	s_cselect_b32 s98, 0x50, s98
	s_cselect_b32 s99, 0, 0x58
	s_load_dwordx2 s[88:89], s[100:101], s98
	s_cmp_eq_u32 s99, 0
	s_cbranch_scc0 .Lcv_s1b_s
	s_bfe_u32 s99, s2, 0x50003
	s_cmp_lt_u32 s99, 16
	s_cselect_b32 s99, 64, 0x48

; #define MX3(a, b, c) __builtin_fmaxf(__builtin_fmaxf((a), (b)), (c))
; template <int G> __device__ __forceinline__ void par_gap(f32x16& C0, f32x16& C1, float& ma, float& mb, float mn) {
;   if constexpr (G == 0) { ma = MX3(C0[0], C0[1], C1[0]); mb = MX3(C0[2], C0[3], C1[1]); ma = MX3(ma, C1[2], C1[3]); ma = MX3(ma, C0[4], C0[5]); }
;   else if constexpr (G == 1) { mb = MX3(mb, C0[6], C0[7]); ma = MX3(ma, C1[4], C1[5]); mb = MX3(mb, C1[6], C1[7]); ma = MX3(ma, C0[8], C0[9]); }
;   else if constexpr (G == 2) { mb = MX3(mb, C0[10], C0[11]); ma = MX3(ma, C1[8], C1[9]); mb = MX3(mb, C1[10], C1[11]); ma = MX3(ma, C0[12], C0[13]); }
;   else if constexpr (G == 3) { mb = MX3(mb, C0[14], C0[15]); ma = MX3(ma, C1[12], C1[13]); mb = MX3(mb, C1[14], C1[15]); }
.Lcv_inc:
	s_add_i32 s87, s87, 1
.Lcv_done:
	ds_read_b64_tr_b16 v[150:151], v167 offset:16384
	ds_read_b64_tr_b16 v[152:153], v167 offset:18432
	ds_read_b64_tr_b16 v[154:155], v167 offset:20480
	ds_read_b64_tr_b16 v[156:157], v167 offset:22528
	ds_read_b64_tr_b16 v[158:159], v167 offset:24576
	ds_read_b64_tr_b16 v[160:161], v167 offset:26624
	ds_read_b64_tr_b16 v[208:209], v167 offset:28672
	ds_read_b64_tr_b16 v[210:211], v167 offset:30720
	v_max_f32_e32 v1, v69, v69
	v_max_f32_e32 v248, v68, v68
	v_max_f32_e32 v1, v248, v1
	v_max3_f32 v248, v70, v71, v85
	v_max3_f32 v1, v1, v84, v86
	v_max3_f32 v1, v1, v87, v72
	v_max3_f32 v248, v248, v74, v75
	v_max3_f32 v1, v1, v73, v88
	v_max3_f32 v248, v248, v90, v91
	s_waitcnt lgkmcnt(6)
	v_mfma_f32_32x32x16_bf16 v[4:19], v[100:103], v[150:153], v[4:19]
	ds_read_b64_tr_b16 v[212:213], v167 offset:16896
	ds_read_b64_tr_b16 v[214:215], v167 offset:18944
	v_max3_f32 v1, v1, v89, v76
	v_max3_f32 v248, v248, v78, v79
	v_max3_f32 v1, v1, v77, v92
	s_waitcnt lgkmcnt(6)
	v_mfma_f32_32x32x16_bf16 v[4:19], v[104:107], v[154:157], v[4:19]
	ds_read_b64_tr_b16 v[150:151], v167 offset:20992
	ds_read_b64_tr_b16 v[152:153], v167 offset:23040
	v_max3_f32 v248, v248, v94, v95
	v_max3_f32 v1, v1, v93, v80
	v_max3_f32 v248, v248, v82, v83
	s_waitcnt lgkmcnt(6)
	v_mfma_f32_32x32x16_bf16 v[4:19], v[108:111], v[158:161], v[4:19]
	ds_read_b64_tr_b16 v[154:155], v167 offset:25088
	ds_read_b64_tr_b16 v[156:157], v167 offset:27136
	v_max3_f32 v1, v1, v81, v96
	v_max3_f32 v248, v248, v98, v99
	v_max3_f32 v1, v1, v97, v248
	s_waitcnt lgkmcnt(6)
	v_mfma_f32_32x32x16_bf16 v[4:19], v[130:133], v[208:211], v[4:19]
	ds_read_b64_tr_b16 v[158:159], v167 offset:29184
	ds_read_b64_tr_b16 v[160:161], v167 offset:31232
	v_mov_b32_e32 v248, v1
	s_waitcnt lgkmcnt(6)
	v_mfma_f32_32x32x16_bf16 v[52:67], v[100:103], v[212:215], v[52:67]
	ds_read_b64_tr_b16 v[208:209], v167 offset:17408
	ds_read_b64_tr_b16 v[210:211], v167 offset:19456
	v_permlane32_swap_b32_e32 v1, v248
	v_max_f32_e32 v248, v248, v248
	v_max_f32_e32 v1, v1, v1
	v_max_f32_e32 v1, v1, v248
	s_waitcnt lgkmcnt(6)
	v_mfma_f32_32x32x16_bf16 v[52:67], v[104:107], v[150:153], v[52:67]
	ds_read_b64_tr_b16 v[212:213], v167 offset:21504
	ds_read_b64_tr_b16 v[214:215], v167 offset:23552
	v_sub_f32_e32 v248, v1, v140
	v_cmp_ge_f32_e32 vcc, s3, v248
	s_cmp_eq_u64 vcc, exec
	v_mov_b32_e32 v204, 1.0
	s_cbranch_scc0 .LBB0_769
